# LN2 main loop also stops at the last real row (padding tail rows of workgroups 160..255 are never output)
# speedup vs baseline: 1.0058x; 1.0058x over previous
.LBB0_1481:
	s_cmpk_gt_i32 s8, 0x213f
	s_cselect_b64 s[0:1], -1, 0
	s_and_b64 s[10:11], s[0:1], exec
	s_cselect_b32 s10, 14, 16
	s_or_b64 s[0:1], s[6:7], s[0:1]
	s_and_b64 vcc, exec, s[0:1]
	s_cbranch_vccnz .LBB0_1486
	s_ashr_i32 s9, s8, 31
	s_lshl_b64 s[10:11], s[8:9], 13
	v_lshlrev_b32_e32 v128, 3, v222
	s_add_u32 s0, s68, s10
	v_ashrrev_i32_e32 v129, 31, v128
	s_addc_u32 s1, s69, s11
	v_lshlrev_b64 v[162:163], 1, v[128:129]
	v_lshl_add_u64 v[142:143], s[0:1], 0, v[162:163]
	global_load_dwordx4 v[130:133], v[142:143], off offset:1024 nt
	global_load_dwordx4 v[134:137], v[142:143], off offset:2048 nt
	global_load_dwordx4 v[194:197], v[142:143], off offset:3072 nt
	global_load_dwordx4 v[138:141], v[142:143], off nt
	v_add_co_u32_e32 v146, vcc, s14, v142
	v_readlane_b32 s18, v254, 31
	s_nop 0
	v_addc_co_u32_e32 v147, vcc, 0, v143, vcc
	global_load_dwordx4 v[142:145], v[146:147], off nt
	global_load_dwordx4 v[204:207], v[146:147], off offset:1024 nt
	global_load_dwordx4 v[210:213], v[146:147], off offset:2048 nt
	global_load_dwordx4 v[214:217], v[146:147], off offset:3072 nt
	v_readlane_b32 s19, v254, 32
	s_waitcnt vmcnt(7)
	v_lshlrev_b32_e32 v190, 16, v130
	v_and_b32_e32 v191, 0xffff0000, v130
	v_lshlrev_b32_e32 v192, 16, v131
	s_waitcnt vmcnt(4)
	v_lshlrev_b32_e32 v201, 16, v139
	v_lshlrev_b32_e32 v200, 16, v138
	v_and_b32_e32 v209, 0xffff0000, v139
	v_and_b32_e32 v208, 0xffff0000, v138
	v_lshlrev_b32_e32 v203, 16, v141
	v_lshlrev_b32_e32 v202, 16, v140
	v_and_b32_e32 v219, 0xffff0000, v141
	v_and_b32_e32 v218, 0xffff0000, v140
	s_waitcnt vmcnt(2)
	v_lshlrev_b32_e32 v158, 16, v206
	v_and_b32_e32 v159, 0xffff0000, v206
	v_lshlrev_b32_e32 v160, 16, v207
	v_and_b32_e32 v161, 0xffff0000, v207
	v_pk_add_f32 v[188:189], v[200:201], v[208:209]
	v_pk_add_f32 v[206:207], v[202:203], v[218:219]
	v_and_b32_e32 v193, 0xffff0000, v131
	v_add_f32_e32 v131, v188, v189
	v_pk_add_f32 v[188:189], v[206:207], v[206:207] op_sel_hi:[0,1]
	v_lshlrev_b32_e32 v182, 16, v132
	v_and_b32_e32 v186, 0xffff0000, v132
	v_lshlrev_b32_e32 v180, 16, v133
	v_and_b32_e32 v184, 0xffff0000, v133
	v_add_f32_e32 v183, v190, v191
	v_add_f32_e32 v187, v192, v193
	v_add_f32_e32 v185, 0, v131
	v_mov_b32_e32 v181, v189
	v_lshlrev_b32_e32 v199, 16, v135
	v_lshlrev_b32_e32 v198, 16, v134
	v_and_b32_e32 v221, 0xffff0000, v135
	v_and_b32_e32 v220, 0xffff0000, v134
	v_pk_add_f32 v[206:207], v[182:183], v[186:187]
	v_pk_add_f32 v[188:189], v[180:181], v[184:185]
	v_lshlrev_b32_e32 v176, 16, v142
	v_and_b32_e32 v177, 0xffff0000, v142
	v_lshlrev_b32_e32 v170, 16, v144
	v_and_b32_e32 v174, 0xffff0000, v144
	s_waitcnt vmcnt(1)
	v_lshlrev_b32_e32 v144, 16, v210
	v_and_b32_e32 v148, 0xffff0000, v210
	v_lshlrev_b32_e32 v142, 16, v211
	v_and_b32_e32 v146, 0xffff0000, v211
	v_pk_add_f32 v[210:211], v[198:199], v[220:221]
	v_pk_add_f32 v[188:189], v[206:207], v[188:189]
	v_lshlrev_b32_e32 v164, 16, v136
	v_and_b32_e32 v165, 0xffff0000, v136
	v_lshlrev_b32_e32 v166, 16, v137
	v_and_b32_e32 v167, 0xffff0000, v137
	v_pk_add_f32 v[210:211], v[210:211], v[210:211] op_sel_hi:[0,1]
	v_pk_add_f32 v[188:189], v[188:189], v[188:189] op_sel_hi:[0,1]
	v_lshlrev_b32_e32 v152, 16, v194
	v_and_b32_e32 v156, 0xffff0000, v194
	v_lshlrev_b32_e32 v150, 16, v195
	v_and_b32_e32 v154, 0xffff0000, v195
	v_add_f32_e32 v153, v164, v165
	v_add_f32_e32 v157, v166, v167
	v_mov_b32_e32 v151, v211
	v_mov_b32_e32 v155, v189
	v_lshlrev_b32_e32 v195, 16, v197
	s_waitcnt vmcnt(0)
	v_lshlrev_b32_e32 v138, 16, v214
	v_and_b32_e32 v139, 0xffff0000, v214
	v_lshlrev_b32_e32 v140, 16, v215
	v_and_b32_e32 v141, 0xffff0000, v215
	v_lshlrev_b32_e32 v132, 16, v216
	v_and_b32_e32 v136, 0xffff0000, v216
	v_lshlrev_b32_e32 v130, 16, v217
	v_and_b32_e32 v134, 0xffff0000, v217
	v_pk_add_f32 v[214:215], v[152:153], v[156:157]
	v_pk_add_f32 v[188:189], v[150:151], v[154:155]
	v_lshlrev_b32_e32 v194, 16, v196
	v_and_b32_e32 v217, 0xffff0000, v197
	v_and_b32_e32 v216, 0xffff0000, v196
	v_pk_add_f32 v[188:189], v[214:215], v[188:189]
	v_pk_add_f32 v[196:197], v[194:195], v[216:217]
	v_lshlrev_b32_e32 v178, 16, v143
	v_and_b32_e32 v179, 0xffff0000, v143
	v_pk_add_f32 v[188:189], v[188:189], v[188:189] op_sel_hi:[0,1]
	v_pk_add_f32 v[196:197], v[196:197], v[196:197] op_sel_hi:[0,1]
	v_lshlrev_b32_e32 v168, 16, v145
	v_and_b32_e32 v172, 0xffff0000, v145
	v_add_f32_e32 v171, v176, v177
	v_add_f32_e32 v175, v178, v179
	v_mov_b32_e32 v169, v197
	v_mov_b32_e32 v173, v189
	v_pk_add_f32 v[206:207], v[170:171], v[174:175]
	v_pk_add_f32 v[188:189], v[168:169], v[172:173]
	v_lshlrev_b32_e32 v197, 16, v205
	v_lshlrev_b32_e32 v196, 16, v204
	v_and_b32_e32 v211, 0xffff0000, v205
	v_and_b32_e32 v210, 0xffff0000, v204
	v_pk_add_f32 v[188:189], v[206:207], v[188:189]
	v_pk_add_f32 v[204:205], v[196:197], v[210:211]
	v_pk_add_f32 v[188:189], v[188:189], v[188:189] op_sel_hi:[0,1]
	v_pk_add_f32 v[204:205], v[204:205], v[204:205] op_sel_hi:[0,1]
	v_add_f32_e32 v145, v158, v159
	v_add_f32_e32 v149, v160, v161
	v_mov_b32_e32 v143, v205
	v_mov_b32_e32 v147, v189
	v_pk_add_f32 v[206:207], v[144:145], v[148:149]
	v_pk_add_f32 v[188:189], v[142:143], v[146:147]
	v_add_f32_e32 v133, v138, v139
	v_pk_add_f32 v[188:189], v[206:207], v[188:189]
	v_and_b32_e32 v207, 0xffff0000, v213
	v_pk_add_f32 v[204:205], v[188:189], v[188:189] op_sel_hi:[0,1]
	v_lshlrev_b32_e32 v189, 16, v213
	v_lshlrev_b32_e32 v188, 16, v212
	v_and_b32_e32 v206, 0xffff0000, v212
	v_pk_add_f32 v[212:213], v[188:189], v[206:207]
	v_add_f32_e32 v137, v140, v141
	v_pk_add_f32 v[212:213], v[212:213], v[212:213] op_sel_hi:[0,1]
	v_mov_b32_e32 v131, v213
	v_mov_b32_e32 v135, v205
	v_pk_add_f32 v[214:215], v[132:133], v[136:137]
	v_pk_add_f32 v[204:205], v[130:131], v[134:135]
	v_and_b32_e32 v135, 64, v226
	v_pk_add_f32 v[204:205], v[214:215], v[204:205]
	v_xor_b32_e32 v133, 16, v226
	v_add_f32_e32 v131, v204, v205
	v_add_u32_e32 v135, 64, v135
	v_cmp_lt_i32_e32 vcc, v133, v135
	v_add_f32_dpp v131, v131, v131 quad_perm:[1,0,3,2] row_mask:0xf bank_mask:0xf bound_ctrl:1
	s_nop 0
	v_cndmask_b32_e32 v133, v226, v133, vcc
	v_add_f32_dpp v131, v131, v131 quad_perm:[2,3,0,1] row_mask:0xf bank_mask:0xf bound_ctrl:1
	v_lshlrev_b32_e32 v137, 2, v133
	s_nop 0
	v_add_f32_dpp v131, v131, v131 row_half_mirror row_mask:0xf bank_mask:0xf bound_ctrl:1
	s_nop 1
	v_add_f32_dpp v131, v131, v131 row_mirror row_mask:0xf bank_mask:0xf bound_ctrl:1
	ds_bpermute_b32 v133, v137, v131
	s_waitcnt lgkmcnt(0)
	v_add_f32_e32 v131, v131, v133
	v_xor_b32_e32 v133, 32, v226
	v_cmp_lt_i32_e32 vcc, v133, v135
	s_nop 1
	v_cndmask_b32_e32 v133, v226, v133, vcc
	v_lshlrev_b32_e32 v135, 2, v133
	ds_bpermute_b32 v133, v135, v131
	s_waitcnt lgkmcnt(0)
	v_add_f32_e32 v131, v131, v133
	v_fmac_f32_e32 v208, 0xb9800000, v131
	v_fmac_f32_e32 v209, 0xb9800000, v131
	v_fmac_f32_e32 v201, 0xb9800000, v131
	v_fmac_f32_e32 v200, 0xb9800000, v131
	v_mov_b32_e32 v204, v201
	v_mov_b32_e32 v205, v209
	v_mov_b32_e32 v201, v208
	v_pk_mul_f32 v[212:213], v[204:205], v[204:205]
	v_pk_mul_f32 v[208:209], v[200:201], v[200:201]
	v_fmac_f32_e32 v218, 0xb9800000, v131
	v_pk_mov_b32 v[214:215], v[208:209], v[212:213] op_sel:[1,0]
	v_mov_b32_e32 v209, v213
	v_pk_add_f32 v[208:209], v[214:215], v[208:209]
	v_fmac_f32_e32 v219, 0xb9800000, v131
	v_fmac_f32_e32 v203, 0xb9800000, v131
	v_pk_add_f32 v[212:213], v[208:209], v[208:209] op_sel_hi:[0,1]
	v_fmac_f32_e32 v202, 0xb9800000, v131
	v_mov_b32_e32 v208, v203
	v_mov_b32_e32 v209, v219
	v_mov_b32_e32 v203, v218
	v_pk_mul_f32 v[214:215], v[208:209], v[208:209]
	v_pk_mul_f32 v[218:219], v[202:203], v[202:203]
	v_fmac_f32_e32 v190, 0xb9800000, v131
	v_pk_mov_b32 v[228:229], v[218:219], v[214:215] op_sel:[1,0]
	v_mov_b32_e32 v219, v215
	v_fmac_f32_e32 v191, 0xb9800000, v131
	v_fmac_f32_e32 v192, 0xb9800000, v131
	v_mul_f32_e32 v212, v190, v190
	v_pk_add_f32 v[214:215], v[228:229], v[218:219]
	v_fmac_f32_e32 v193, 0xb9800000, v131
	v_pk_fma_f32 v[218:219], v[190:191], v[190:191], v[212:213] op_sel_hi:[1,1,0]
	v_mul_f32_e32 v212, v192, v192
	v_pk_add_f32 v[214:215], v[214:215], v[214:215] op_sel_hi:[0,1]
	v_pk_fma_f32 v[228:229], v[192:193], v[192:193], v[212:213] op_sel_hi:[1,1,0]
	v_fmac_f32_e32 v184, 0xb9800000, v131
	v_fmac_f32_e32 v180, 0xb9800000, v131
	v_fmac_f32_e32 v186, 0xb9800000, v131
	v_fmac_f32_e32 v182, 0xb9800000, v131
	v_mul_f32_e32 v218, v182, v182
	v_mul_f32_e32 v228, v186, v186
	v_mul_f32_e32 v212, v180, v180
	v_mul_f32_e32 v214, v184, v184
	v_pk_add_f32 v[218:219], v[218:219], v[228:229]
	v_pk_add_f32 v[212:213], v[212:213], v[214:215]
	v_fmac_f32_e32 v220, 0xb9800000, v131
	v_fmac_f32_e32 v221, 0xb9800000, v131
	v_fmac_f32_e32 v199, 0xb9800000, v131
	v_pk_add_f32 v[212:213], v[218:219], v[212:213]
	v_fmac_f32_e32 v198, 0xb9800000, v131
	v_mov_b32_e32 v214, v199
	v_mov_b32_e32 v215, v221
	v_mov_b32_e32 v199, v220
	v_pk_add_f32 v[212:213], v[212:213], v[212:213] op_sel_hi:[0,1]
	v_pk_mul_f32 v[218:219], v[214:215], v[214:215]
	v_pk_mul_f32 v[220:221], v[198:199], v[198:199]
	v_fmac_f32_e32 v164, 0xb9800000, v131
	v_pk_mov_b32 v[228:229], v[220:221], v[218:219] op_sel:[1,0]
	v_mov_b32_e32 v221, v219
	v_fmac_f32_e32 v165, 0xb9800000, v131
	v_fmac_f32_e32 v166, 0xb9800000, v131
	v_mul_f32_e32 v212, v164, v164
	v_pk_add_f32 v[218:219], v[228:229], v[220:221]
	v_fmac_f32_e32 v167, 0xb9800000, v131
	v_pk_fma_f32 v[220:221], v[164:165], v[164:165], v[212:213] op_sel_hi:[1,1,0]
	v_mul_f32_e32 v212, v166, v166
	v_pk_add_f32 v[218:219], v[218:219], v[218:219] op_sel_hi:[0,1]
	v_pk_fma_f32 v[228:229], v[166:167], v[166:167], v[212:213] op_sel_hi:[1,1,0]
	v_fmac_f32_e32 v154, 0xb9800000, v131
	v_fmac_f32_e32 v150, 0xb9800000, v131
	v_fmac_f32_e32 v156, 0xb9800000, v131
	v_fmac_f32_e32 v152, 0xb9800000, v131
	v_mul_f32_e32 v220, v152, v152
	v_mul_f32_e32 v228, v156, v156
	v_mul_f32_e32 v218, v150, v150
	v_mul_f32_e32 v212, v154, v154
	v_pk_add_f32 v[220:221], v[220:221], v[228:229]
	v_pk_add_f32 v[212:213], v[218:219], v[212:213]
	v_fmac_f32_e32 v216, 0xb9800000, v131
	v_fmac_f32_e32 v217, 0xb9800000, v131
	v_fmac_f32_e32 v195, 0xb9800000, v131
	v_pk_add_f32 v[212:213], v[220:221], v[212:213]
	v_fmac_f32_e32 v194, 0xb9800000, v131
	v_mov_b32_e32 v218, v195
	v_mov_b32_e32 v219, v217
	v_mov_b32_e32 v195, v216
	v_pk_add_f32 v[212:213], v[212:213], v[212:213] op_sel_hi:[0,1]
	v_pk_mul_f32 v[220:221], v[218:219], v[218:219]
	v_pk_mul_f32 v[216:217], v[194:195], v[194:195]
	v_fmac_f32_e32 v176, 0xb9800000, v131
	v_pk_mov_b32 v[228:229], v[216:217], v[220:221] op_sel:[1,0]
	v_mov_b32_e32 v217, v221
	v_fmac_f32_e32 v177, 0xb9800000, v131
	v_fmac_f32_e32 v178, 0xb9800000, v131
	v_mul_f32_e32 v212, v176, v176
	v_pk_add_f32 v[216:217], v[228:229], v[216:217]
	v_fmac_f32_e32 v179, 0xb9800000, v131
	v_pk_fma_f32 v[220:221], v[176:177], v[176:177], v[212:213] op_sel_hi:[1,1,0]
	v_mul_f32_e32 v212, v178, v178
	v_pk_add_f32 v[216:217], v[216:217], v[216:217] op_sel_hi:[0,1]
	v_pk_fma_f32 v[228:229], v[178:179], v[178:179], v[212:213] op_sel_hi:[1,1,0]
	v_fmac_f32_e32 v172, 0xb9800000, v131
	v_fmac_f32_e32 v168, 0xb9800000, v131
	v_fmac_f32_e32 v174, 0xb9800000, v131
	v_fmac_f32_e32 v170, 0xb9800000, v131
	v_mul_f32_e32 v220, v170, v170
	v_mul_f32_e32 v228, v174, v174
	v_mul_f32_e32 v216, v168, v168
	v_mul_f32_e32 v212, v172, v172
	v_fmac_f32_e32 v210, 0xb9800000, v131
	v_fmac_f32_e32 v211, 0xb9800000, v131
	v_fmac_f32_e32 v197, 0xb9800000, v131
	v_pk_add_f32 v[220:221], v[220:221], v[228:229]
	v_pk_add_f32 v[212:213], v[216:217], v[212:213]
	v_fmac_f32_e32 v196, 0xb9800000, v131
	v_mov_b32_e32 v216, v197
	v_mov_b32_e32 v217, v211
	v_mov_b32_e32 v197, v210
	v_pk_add_f32 v[212:213], v[220:221], v[212:213]
	v_pk_mul_f32 v[220:221], v[216:217], v[216:217]
	v_pk_mul_f32 v[210:211], v[196:197], v[196:197]
	v_fmac_f32_e32 v158, 0xb9800000, v131
	v_pk_mov_b32 v[228:229], v[210:211], v[220:221] op_sel:[1,0]
	v_mov_b32_e32 v211, v221
	v_pk_add_f32 v[210:211], v[228:229], v[210:211]
	v_fmac_f32_e32 v159, 0xb9800000, v131
	v_pk_add_f32 v[210:211], v[210:211], v[210:211] op_sel_hi:[0,1]
	v_fmac_f32_e32 v160, 0xb9800000, v131
	v_mul_f32_e32 v210, v158, v158
	v_fmac_f32_e32 v161, 0xb9800000, v131
	v_pk_fma_f32 v[220:221], v[158:159], v[158:159], v[210:211] op_sel_hi:[1,1,0]
	v_mul_f32_e32 v210, v160, v160
	v_pk_add_f32 v[212:213], v[212:213], v[212:213] op_sel_hi:[0,1]
	v_pk_fma_f32 v[228:229], v[160:161], v[160:161], v[210:211] op_sel_hi:[1,1,0]
	v_fmac_f32_e32 v146, 0xb9800000, v131
	v_fmac_f32_e32 v142, 0xb9800000, v131
	v_fmac_f32_e32 v148, 0xb9800000, v131
	v_fmac_f32_e32 v144, 0xb9800000, v131
	v_mul_f32_e32 v220, v144, v144
	v_mul_f32_e32 v228, v148, v148
	v_mul_f32_e32 v210, v142, v142
	v_mul_f32_e32 v212, v146, v146
	v_pk_add_f32 v[220:221], v[220:221], v[228:229]
	v_pk_add_f32 v[210:211], v[210:211], v[212:213]
	v_fmac_f32_e32 v206, 0xb9800000, v131
	v_fmac_f32_e32 v207, 0xb9800000, v131
	v_fmac_f32_e32 v189, 0xb9800000, v131
	v_pk_add_f32 v[210:211], v[220:221], v[210:211]
	v_fmac_f32_e32 v188, 0xb9800000, v131
	v_mov_b32_e32 v220, v189
	v_mov_b32_e32 v221, v207
	v_mov_b32_e32 v189, v206
	v_pk_mul_f32 v[212:213], v[220:221], v[220:221]
	v_pk_mul_f32 v[206:207], v[188:189], v[188:189]
	v_fmac_f32_e32 v138, 0xb9800000, v131
	v_pk_mov_b32 v[228:229], v[206:207], v[212:213] op_sel:[1,0]
	v_mov_b32_e32 v207, v213
	v_pk_add_f32 v[206:207], v[228:229], v[206:207]
	v_fmac_f32_e32 v139, 0xb9800000, v131
	v_pk_add_f32 v[206:207], v[206:207], v[206:207] op_sel_hi:[0,1]
	v_fmac_f32_e32 v140, 0xb9800000, v131
	v_mul_f32_e32 v206, v138, v138
	v_fmac_f32_e32 v141, 0xb9800000, v131
	v_pk_fma_f32 v[212:213], v[138:139], v[138:139], v[206:207] op_sel_hi:[1,1,0]
	v_mul_f32_e32 v206, v140, v140
	v_pk_add_f32 v[210:211], v[210:211], v[210:211] op_sel_hi:[0,1]
	v_pk_fma_f32 v[228:229], v[140:141], v[140:141], v[206:207] op_sel_hi:[1,1,0]
	v_fmac_f32_e32 v134, 0xb9800000, v131
	v_fmac_f32_e32 v130, 0xb9800000, v131
	v_fmac_f32_e32 v136, 0xb9800000, v131
	v_fmac_f32_e32 v132, 0xb9800000, v131
	v_mul_f32_e32 v212, v132, v132
	v_mul_f32_e32 v228, v136, v136
	v_mul_f32_e32 v206, v130, v130
	v_mul_f32_e32 v210, v134, v134
	v_pk_add_f32 v[212:213], v[212:213], v[228:229]
	v_pk_add_f32 v[206:207], v[206:207], v[210:211]
	v_mov_b32_e32 v183, v186
	v_pk_add_f32 v[206:207], v[212:213], v[206:207]
	v_mov_b32_e32 v181, v184
	v_add_f32_e32 v131, v206, v207
	v_mov_b32_e32 v153, v156
	v_mov_b32_e32 v151, v154
	v_add_f32_dpp v131, v131, v131 quad_perm:[1,0,3,2] row_mask:0xf bank_mask:0xf bound_ctrl:1
	v_mov_b32_e32 v171, v174
	v_mov_b32_e32 v169, v172
	v_add_f32_dpp v131, v131, v131 quad_perm:[2,3,0,1] row_mask:0xf bank_mask:0xf bound_ctrl:1
	s_nop 1
	v_add_f32_dpp v131, v131, v131 row_half_mirror row_mask:0xf bank_mask:0xf bound_ctrl:1
	s_nop 1
	v_add_f32_dpp v131, v131, v131 row_mirror row_mask:0xf bank_mask:0xf bound_ctrl:1
	ds_bpermute_b32 v133, v137, v131
	s_waitcnt lgkmcnt(0)
	v_add_f32_e32 v131, v131, v133
	ds_bpermute_b32 v133, v135, v131
	s_waitcnt lgkmcnt(0)
	v_add_f32_e32 v131, v131, v133
	v_fmamk_f32 v131, v131, 0x39800000, v224
	v_mul_f32_e32 v133, 0x4f800000, v131
	v_cmp_gt_f32_e32 vcc, s15, v131
	s_nop 1
	v_cndmask_b32_e32 v131, v131, v133, vcc
	v_sqrt_f32_e32 v133, v131
	s_nop 0
	v_add_u32_e32 v143, -1, v133
	v_fma_f32 v145, -v143, v133, v131
	v_cmp_ge_f32_e64 s[0:1], 0, v145
	v_add_u32_e32 v145, 1, v133
	s_nop 0
	v_cndmask_b32_e64 v143, v133, v143, s[0:1]
	v_fma_f32 v133, -v145, v133, v131
	v_cmp_lt_f32_e64 s[0:1], 0, v133
	s_nop 1
	v_cndmask_b32_e64 v133, v143, v145, s[0:1]
	v_mul_f32_e32 v143, 0x37800000, v133
	v_cndmask_b32_e32 v133, v133, v143, vcc
	v_cmp_class_f32_e32 vcc, v131, v225
	s_nop 1
	v_cndmask_b32_e32 v131, v133, v131, vcc
	v_div_scale_f32 v133, s[0:1], v131, v131, 1.0
	v_rcp_f32_e32 v143, v133
	s_add_u32 s0, s84, s10
	s_addc_u32 s1, s19, s11
	v_lshl_add_u64 v[230:231], s[0:1], 0, v[162:163]
	v_fma_f32 v145, -v133, v143, 1.0
	v_fmac_f32_e32 v143, v145, v143
	v_div_scale_f32 v145, vcc, 1.0, v131, 1.0
	v_mul_f32_e32 v147, v145, v143
	v_fma_f32 v149, -v133, v147, v145
	v_fmac_f32_e32 v147, v149, v143
	v_fma_f32 v133, -v133, v147, v145
	v_div_fmas_f32 v133, v133, v143, v147
	v_div_fixup_f32 v228, v133, v131, 1.0
	v_pk_mul_f32 v[200:201], v[200:201], v[228:229] op_sel_hi:[1,0]
	v_pk_mul_f32 v[204:205], v[204:205], v[228:229] op_sel_hi:[1,0]
	v_pk_fma_f32 v[206:207], v[4:5], v[200:201], v[12:13]
	v_pk_mul_f32 v[200:201], v[202:203], v[228:229] op_sel_hi:[1,0]
	v_pk_mul_f32 v[202:203], v[208:209], v[228:229] op_sel_hi:[1,0]
	v_pk_fma_f32 v[204:205], v[6:7], v[204:205], v[14:15]
	v_pk_fma_f32 v[210:211], v[2:3], v[202:203], v[10:11]
	v_pk_fma_f32 v[212:213], v[0:1], v[200:201], v[8:9]
	v_pk_mul_f32 v[162:163], v[190:191], v[228:229] op_sel_hi:[1,0]
	v_cvt_pk_bf16_f32 v200, v206, v207
	v_cvt_pk_bf16_f32 v201, v204, v205
	v_cvt_pk_bf16_f32 v202, v212, v213
	v_cvt_pk_bf16_f32 v203, v210, v211
	v_pk_mul_f32 v[190:191], v[192:193], v[228:229] op_sel_hi:[1,0]
	v_pk_fma_f32 v[192:193], v[20:21], v[162:163], v[28:29]
	v_pk_mul_f32 v[162:163], v[182:183], v[228:229] op_sel_hi:[1,0]
	v_pk_mul_f32 v[180:181], v[180:181], v[228:229] op_sel_hi:[1,0]
	global_store_dwordx4 v[230:231], v[200:203], off
	v_pk_fma_f32 v[190:191], v[22:23], v[190:191], v[30:31]
	v_pk_fma_f32 v[208:209], v[16:17], v[162:163], v[24:25]
	v_pk_fma_f32 v[202:203], v[18:19], v[180:181], v[26:27]
	v_cvt_pk_bf16_f32 v180, v192, v193
	v_cvt_pk_bf16_f32 v181, v190, v191
	v_cvt_pk_bf16_f32 v182, v208, v209
	v_cvt_pk_bf16_f32 v183, v202, v203
	v_pk_mul_f32 v[162:163], v[198:199], v[228:229] op_sel_hi:[1,0]
	global_store_dwordx4 v[230:231], v[180:183], off offset:1024
	v_pk_mul_f32 v[152:153], v[152:153], v[228:229] op_sel_hi:[1,0]
	v_pk_mul_f32 v[150:151], v[150:151], v[228:229] op_sel_hi:[1,0]
	v_pk_mul_f32 v[180:181], v[214:215], v[228:229] op_sel_hi:[1,0]
	v_pk_fma_f32 v[182:183], v[56:57], v[162:163], v[68:69]
	v_pk_mul_f32 v[162:163], v[164:165], v[228:229] op_sel_hi:[1,0]
	v_pk_mul_f32 v[164:165], v[166:167], v[228:229] op_sel_hi:[1,0]
	v_pk_fma_f32 v[180:181], v[58:59], v[180:181], v[70:71]
	v_pk_fma_f32 v[198:199], v[34:35], v[164:165], v[46:47]
	v_pk_fma_f32 v[200:201], v[32:33], v[162:163], v[44:45]
	v_cvt_pk_bf16_f32 v162, v182, v183
	v_cvt_pk_bf16_f32 v163, v180, v181
	v_cvt_pk_bf16_f32 v164, v200, v201
	v_cvt_pk_bf16_f32 v165, v198, v199
	v_max_f32_e64 v143, |v210|, |v211|
	global_store_dwordx4 v[230:231], v[162:165], off offset:2048
	v_max_f32_e64 v131, |v206|, |v207|
	v_max_f32_e64 v133, |v204|, |v205|
	v_pk_fma_f32 v[162:163], v[38:39], v[150:151], v[50:51]
	v_pk_fma_f32 v[164:165], v[36:37], v[152:153], v[48:49]
	v_pk_mul_f32 v[150:151], v[194:195], v[228:229] op_sel_hi:[1,0]
	v_pk_mul_f32 v[152:153], v[218:219], v[228:229] op_sel_hi:[1,0]
	v_max3_f32 v143, |v212|, |v213|, v143
	v_max_f32_e64 v145, |v202|, |v203|
	v_pk_fma_f32 v[184:185], v[42:43], v[152:153], v[54:55]
	v_pk_fma_f32 v[186:187], v[40:41], v[150:151], v[52:53]
	v_max3_f32 v131, v131, v133, v143
	v_max_f32_e64 v133, |v192|, |v193|
	v_max_f32_e64 v143, |v190|, |v191|
	v_max3_f32 v145, |v208|, |v209|, v145
	v_cvt_pk_bf16_f32 v150, v164, v165
	v_cvt_pk_bf16_f32 v151, v162, v163
	v_cvt_pk_bf16_f32 v152, v186, v187
	v_cvt_pk_bf16_f32 v153, v184, v185
	v_max3_f32 v133, v133, v143, v145
	v_max_f32_e64 v145, |v198|, |v199|
	global_store_dwordx4 v[230:231], v[150:153], off offset:3072
	v_pk_mul_f32 v[154:155], v[170:171], v[228:229] op_sel_hi:[1,0]
	v_pk_mul_f32 v[156:157], v[168:169], v[228:229] op_sel_hi:[1,0]
	v_pk_mul_f32 v[152:153], v[176:177], v[228:229] op_sel_hi:[1,0]
	v_pk_mul_f32 v[150:151], v[178:179], v[228:229] op_sel_hi:[1,0]
	v_max3_f32 v131, v131, 0, v133
	v_max_f32_e64 v133, |v182|, |v183|
	v_max_f32_e64 v143, |v180|, |v181|
	v_max3_f32 v145, |v200|, |v201|, v145
	v_max_f32_e64 v147, |v184|, |v185|
	v_pk_fma_f32 v[150:151], v[62:63], v[150:151], v[74:75]
	v_pk_fma_f32 v[152:153], v[60:61], v[152:153], v[72:73]
	v_pk_fma_f32 v[166:167], v[66:67], v[156:157], v[78:79]
	v_pk_fma_f32 v[168:169], v[64:65], v[154:155], v[76:77]
	v_add_co_u32_e32 v174, vcc, s14, v230
	v_max3_f32 v133, v133, v143, v145
	v_max_f32_e64 v143, |v164|, |v165|
	v_max_f32_e64 v145, |v162|, |v163|
	v_max3_f32 v147, |v186|, |v187|, v147
	v_cvt_pk_bf16_f32 v154, v152, v153
	v_cvt_pk_bf16_f32 v155, v150, v151
	v_cvt_pk_bf16_f32 v156, v168, v169
	v_cvt_pk_bf16_f32 v157, v166, v167
	v_addc_co_u32_e32 v175, vcc, 0, v231, vcc
	v_pk_mul_f32 v[170:171], v[158:159], v[228:229] op_sel_hi:[1,0]
	v_pk_mul_f32 v[158:159], v[160:161], v[228:229] op_sel_hi:[1,0]
	v_max3_f32 v143, v143, v145, v147
	global_store_dwordx4 v[174:175], v[154:157], off
	v_max_f32_e64 v145, |v166|, |v167|
	v_pk_fma_f32 v[158:159], v[86:87], v[158:159], v[94:95]
	v_pk_mul_f32 v[156:157], v[196:197], v[228:229] op_sel_hi:[1,0]
	v_pk_mul_f32 v[154:155], v[216:217], v[228:229] op_sel_hi:[1,0]
	v_max3_f32 v131, v131, v133, v143
	v_max_f32_e64 v133, |v152|, |v153|
	v_max_f32_e64 v143, |v150|, |v151|
	v_max3_f32 v145, |v168|, |v169|, v145
	v_pk_fma_f32 v[154:155], v[82:83], v[154:155], v[90:91]
	v_pk_fma_f32 v[156:157], v[80:81], v[156:157], v[88:89]
	v_pk_fma_f32 v[160:161], v[84:85], v[170:171], v[92:93]
	v_max_f32_e64 v147, |v158|, |v159|
	v_max3_f32 v133, v133, v143, v145
	v_max_f32_e64 v143, |v156|, |v157|
	v_max_f32_e64 v145, |v154|, |v155|
	v_max3_f32 v147, |v160|, |v161|, v147
	v_max3_f32 v143, v143, v145, v147
	v_max3_f32 v176, v131, v133, v143
	v_mov_b32_e32 v145, v148
	v_mov_b32_e32 v143, v146
	v_pk_mul_f32 v[146:147], v[220:221], v[228:229] op_sel_hi:[1,0]
	v_cvt_pk_bf16_f32 v170, v156, v157
	v_cvt_pk_bf16_f32 v171, v154, v155
	v_cvt_pk_bf16_f32 v172, v160, v161
	v_cvt_pk_bf16_f32 v173, v158, v159
	v_pk_mul_f32 v[144:145], v[144:145], v[228:229] op_sel_hi:[1,0]
	v_pk_mul_f32 v[142:143], v[142:143], v[228:229] op_sel_hi:[1,0]
	v_pk_mul_f32 v[148:149], v[188:189], v[228:229] op_sel_hi:[1,0]
	v_pk_fma_f32 v[146:147], v[102:103], v[146:147], v[110:111]
	global_store_dwordx4 v[174:175], v[170:173], off offset:1024
	v_pk_fma_f32 v[142:143], v[98:99], v[142:143], v[106:107]
	v_pk_fma_f32 v[144:145], v[96:97], v[144:145], v[104:105]
	v_pk_fma_f32 v[148:149], v[100:101], v[148:149], v[108:109]
	v_max_f32_e64 v172, |v146|, |v147|
	v_max_f32_e64 v131, |v144|, |v145|
	v_max_f32_e64 v133, |v142|, |v143|
	v_max3_f32 v172, |v148|, |v149|, v172
	v_max3_f32 v177, v131, v133, v172
	v_mov_b32_e32 v131, v134
	v_mov_b32_e32 v133, v136
	v_pk_mul_f32 v[130:131], v[130:131], v[228:229] op_sel_hi:[1,0]
	v_pk_mul_f32 v[172:173], v[138:139], v[228:229] op_sel_hi:[1,0]
	v_pk_mul_f32 v[138:139], v[140:141], v[228:229] op_sel_hi:[1,0]
	v_pk_mul_f32 v[132:133], v[132:133], v[228:229] op_sel_hi:[1,0]
	v_pk_fma_f32 v[130:131], v[118:119], v[130:131], v[126:127]
	v_pk_fma_f32 v[138:139], v[114:115], v[138:139], v[122:123]
	v_pk_fma_f32 v[140:141], v[112:113], v[172:173], v[120:121]
	v_pk_fma_f32 v[132:133], v[116:117], v[132:133], v[124:125]
	v_max_f32_e64 v172, |v130|, |v131|
	v_max_f32_e64 v134, |v140|, |v141|
	v_max_f32_e64 v136, |v138|, |v139|
	v_max3_f32 v172, |v132|, |v133|, v172
	v_max3_f32 v134, v134, v136, v172
	v_max3_f32 v134, v176, v177, v134
	v_mov_b32_e32 v136, 0
	v_cvt_pk_bf16_f32 v170, v144, v145
	v_cvt_pk_bf16_f32 v171, v142, v143
	v_mov_b32_dpp v136, v134 quad_perm:[1,0,3,2] row_mask:0xf bank_mask:0xf
	v_max_f32_e32 v136, v136, v136
	v_max_f32_e32 v134, v134, v136
	v_mov_b32_e32 v136, 0
	v_cvt_pk_bf16_f32 v172, v148, v149
	v_cvt_pk_bf16_f32 v173, v146, v147
	v_mov_b32_dpp v136, v134 quad_perm:[2,3,0,1] row_mask:0xf bank_mask:0xf
	v_max_f32_e32 v136, v136, v136
	v_max_f32_e32 v134, v134, v136
	v_mov_b32_e32 v136, 0
	global_store_dwordx4 v[174:175], v[170:173], off offset:2048
	v_cmp_eq_u32_e32 vcc, 0, v222
	v_mov_b32_dpp v136, v134 row_half_mirror row_mask:0xf bank_mask:0xf
	v_max_f32_e32 v136, v136, v136
	v_max_f32_e32 v134, v134, v136
	v_mov_b32_e32 v136, 0
	s_nop 1
	v_mov_b32_dpp v136, v134 row_mirror row_mask:0xf bank_mask:0xf
	v_max_f32_e32 v136, v136, v136
	v_max_f32_e32 v136, v134, v136
	ds_bpermute_b32 v137, v137, v136
	v_cvt_pk_bf16_f32 v134, v140, v141
	s_waitcnt lgkmcnt(0)
	v_max_f32_e32 v137, v137, v137
	v_max_f32_e32 v170, v136, v137
	ds_bpermute_b32 v171, v135, v170
	v_cvt_pk_bf16_f32 v135, v138, v139
	v_cvt_pk_bf16_f32 v136, v132, v133
	v_cvt_pk_bf16_f32 v137, v130, v131
	global_store_dwordx4 v[174:175], v[134:137], off offset:3072
	s_waitcnt lgkmcnt(0)
	s_nop 0
	v_max_f32_e32 v134, v171, v171
	v_max_f32_e32 v134, v170, v134
	s_and_saveexec_b64 s[0:1], vcc
	s_cbranch_execz .LBB0_1484
	s_lshl_b64 s[10:11], s[8:9], 2
	s_add_u32 s10, s4, s10
	s_addc_u32 s11, s5, s11
	v_mul_f32_e32 v135, 0x3c010204, v134
	global_store_dword v223, v135, s[10:11]
